# GEMM phase prologues: the second stage-DMA group issues without waiting for the first to land (pacing wait removed, barrier kept)
# speedup vs baseline: 1.0048x; 1.0032x over previous
; __device__ __forceinline__ int prow0(int pm) { return (pm >> 4) * LP + PADR + (pm & 15) * 256; }
;     __device__ __forceinline__ void prep(int pm, int par, LAS unsigned char* lds) const { if (fold) prep_rowstats(stat, pm, par, lds); }
;     __device__ __forceinline__ void prep(int pm, int par, LAS unsigned char* lds) const { if (!ident) prep_rowstats(stat, pm, par, lds); }
;     __device__ __forceinline__ void prep(int pm, int par, LAS unsigned char* lds) const { prep_rowstats(stat, pm, par, lds); }
; #define G_STAGE(bufoff, gbase) do { _Pragma("unroll") for (int _i = 0; _i < 2; ++_i) \
;         __builtin_amdgcn_global_load_lds((const unsigned*)((const char*)(gbase) + voff[_i]), (LAS unsigned*)(lds + (bufoff) + ldsw + _i * 8192), 16, 0, 0); } while (0)
; #define G_WAIT_V(n) asm volatile("s_waitcnt vmcnt(" #n ")" ::: "memory")
; #define G_BAR __builtin_amdgcn_s_barrier()
; template <class Epi>
; __device__ __forceinline__ void gemm_phase(LAS unsigned char* lds, const bf16_t* Ag, const bf16_t* Btg, const int K, const int nM, const int nN, const Epi& E) {
;     ...
;     for (int i = 0; i < 2; ++i) { int R, C; stage_rc(tid * 16 + i * 8192, R, C); voff[i] = (unsigned)(R * K + C) * 2u; }
;     const size_t kstep = 128, hstep = (size_t)128 * K * 2, tstep = 2 * hstep;
;     const unsigned ldsw = (unsigned)wid * 1024u;
;     const int aoff = lds_byte(wr * 64 + fr, fq * 8), boff = lds_byte(wc * 32 + fr, fq * 8);
;     ...
;     const size_t rstep = (size_t)K * 2;
;     const char* cA = (const char*)Ag + (size_t)prow0(pm) * rstep; const char* cB = (const char*)Btg + (size_t)pn * tstep;
;     E.prep(pm, par, lds);
;     G_STAGE(G_SB(0, 0), cB); G_STAGE(G_SA(0, 0), cA); G_STAGE(G_SB(0, 1), cB + hstep); G_STAGE(G_SA(0, 1), cA + hstep);
;     if (wr == 1) G_BAR;
;     G_WAIT_V(4); G_BAR;
;     G_STAGE(G_SB(1, 0), cB + kstep); G_STAGE(G_SA(1, 0), cA + kstep); G_STAGE(G_SB(1, 1), cB + hstep + kstep);
;     G_WAIT_V(6); G_BAR;
.LBB0_70:
	v_bfe_u32 v24, v16, 4, 2
	v_and_b32_e32 v23, 15, v16
	v_lshlrev_b32_e32 v25, 4, v24
	v_lshlrev_b32_e32 v16, 2, v16
	s_lshl_b32 s26, s12, 6
	v_lshl_or_b32 v25, v23, 6, v25
	s_lshl_b32 s14, s14, 5
	v_and_b32_e32 v16, 32, v16
	s_lshl_b32 s12, s12, 13
	v_bitop3_b32 v26, v25, s12, v16 bitop3:0xde
	s_and_b32 s12, s14, 0x60
	s_add_i32 m0, s58, 0x18000
	v_lshl_add_u64 v[14:15], v[14:15], 0, s[94:95]
	s_lshl_b32 s14, s12, 7
	s_barrier
	global_load_lds_dwordx4 v[14:15], off
	v_lshl_add_u64 v[12:13], v[12:13], 0, s[94:95]
	s_add_i32 m0, s58, 0x1a000
	s_add_i32 s62, s58, 0x8000
	s_add_i32 s63, s58, 0xa000
	v_bitop3_b32 v175, v25, s14, v16 bitop3:0xde
	global_load_lds_dwordx4 v[12:13], off
	v_lshl_add_u64 v[10:11], v[10:11], 0, s[94:95]
	s_mov_b32 m0, s62
	s_add_u32 s14, s52, 0x40080
	global_load_lds_dwordx4 v[10:11], off
	v_lshl_add_u64 v[8:9], v[8:9], 0, s[94:95]
	s_mov_b32 m0, s63
	s_addc_u32 s15, s53, 0
	global_load_lds_dwordx4 v[8:9], off
	s_add_i32 m0, s58, 0x1c000
	v_lshl_add_u64 v[8:9], s[14:15], 0, v[0:1]
	global_load_lds_dwordx4 v[8:9], off
	v_lshl_add_u64 v[8:9], s[14:15], 0, v[2:3]
	s_add_i32 m0, s58, 0x1e000
	v_readlane_b32 s14, v253, 51
	global_load_lds_dwordx4 v[8:9], off
	v_lshlrev_b32_e32 v8, 14, v20
	v_and_b32_e32 v8, 0xffff8000, v8
	v_lshl_add_u32 v8, v21, 11, v8
	v_and_b32_e32 v9, 1, v20
	v_lshl_or_b32 v8, v9, 6, v8
	v_lshl_add_u32 v168, v22, 1, v8
	v_lshlrev_b32_e32 v8, 14, v17
	v_and_b32_e32 v8, 0xffff8000, v8
	v_or_b32_e32 v174, s26, v23
	s_waitcnt vmcnt(6)
	s_addk_i32 s26, 0x80
	v_lshl_add_u32 v8, v18, 11, v8
	v_and_b32_e32 v9, 1, v17
	v_readlane_b32 s15, v253, 52
	v_or_b32_e32 v181, s26, v23
	v_lshl_or_b32 v8, v9, 6, v8
	s_mov_b32 s68, s14
	v_readlane_b32 s14, v255, 21
	v_or_b32_e32 v176, 16, v174
	v_or_b32_e32 v179, 32, v174
	v_or_b32_e32 v180, 48, v174
	v_or_b32_e32 v182, 16, v181
	v_or_b32_e32 v183, 32, v181
	v_or_b32_e32 v184, 48, v181
	v_lshl_or_b32 v185, v24, 2, s12
	v_mov_b32_e32 v169, v1
	v_lshl_add_u32 v170, v19, 1, v8
	v_mov_b32_e32 v171, v1
	s_mov_b32 s64, 0
	v_add_u32_e32 v186, 0, v26
	v_readlane_b32 s66, v253, 27
	s_mov_b32 s65, s14
	s_barrier
	v_readlane_b32 s15, v255, 22
	s_branch .LBB0_72

; __device__ __forceinline__ int prow0(int pm) { return (pm >> 4) * LP + PADR + (pm & 15) * 256; }
;     __device__ __forceinline__ void prep(int pm, int par, LAS unsigned char* lds) const { if (fold) prep_rowstats(stat, pm, par, lds); }
;     __device__ __forceinline__ void prep(int pm, int par, LAS unsigned char* lds) const { if (!ident) prep_rowstats(stat, pm, par, lds); }
;     __device__ __forceinline__ void prep(int pm, int par, LAS unsigned char* lds) const { prep_rowstats(stat, pm, par, lds); }
; #define G_STAGE(bufoff, gbase) do { _Pragma("unroll") for (int _i = 0; _i < 2; ++_i) \
;         __builtin_amdgcn_global_load_lds((const unsigned*)((const char*)(gbase) + voff[_i]), (LAS unsigned*)(lds + (bufoff) + ldsw + _i * 8192), 16, 0, 0); } while (0)
; #define G_WAIT_V(n) asm volatile("s_waitcnt vmcnt(" #n ")" ::: "memory")
; #define G_BAR __builtin_amdgcn_s_barrier()
; template <class Epi>
; __device__ __forceinline__ void gemm_phase(LAS unsigned char* lds, const bf16_t* Ag, const bf16_t* Btg, const int K, const int nM, const int nN, const Epi& E) {
;     ...
;     for (int i = 0; i < 2; ++i) { int R, C; stage_rc(tid * 16 + i * 8192, R, C); voff[i] = (unsigned)(R * K + C) * 2u; }
;     const size_t kstep = 128, hstep = (size_t)128 * K * 2, tstep = 2 * hstep;
;     const unsigned ldsw = (unsigned)wid * 1024u;
;     const int aoff = lds_byte(wr * 64 + fr, fq * 8), boff = lds_byte(wc * 32 + fr, fq * 8);
;     ...
;     const size_t rstep = (size_t)K * 2;
;     const char* cA = (const char*)Ag + (size_t)prow0(pm) * rstep; const char* cB = (const char*)Btg + (size_t)pn * tstep;
;     E.prep(pm, par, lds);
;     G_STAGE(G_SB(0, 0), cB); G_STAGE(G_SA(0, 0), cA); G_STAGE(G_SB(0, 1), cB + hstep); G_STAGE(G_SA(0, 1), cA + hstep);
;     if (wr == 1) G_BAR;
;     G_WAIT_V(4); G_BAR;
;     G_STAGE(G_SB(1, 0), cB + kstep); G_STAGE(G_SA(1, 0), cA + kstep); G_STAGE(G_SB(1, 1), cB + hstep + kstep);
;     G_WAIT_V(6); G_BAR;
.LBB0_144:
	s_waitcnt vmcnt(0)
	v_bfe_u32 v26, v8, 4, 2
	v_lshl_add_u64 v[18:19], s[66:67], 0, v[0:1]
	v_mov_b32_e32 v3, v1
	v_and_b32_e32 v17, 15, v8
	v_lshlrev_b32_e32 v27, 4, v26
	v_lshlrev_b32_e32 v8, 2, v8
	v_lshl_add_u64 v[20:21], s[66:67], 0, v[2:3]
	s_and_b32 s90, s14, 3
	s_lshl_b32 s26, s12, 6
	v_lshl_or_b32 v27, v17, 6, v27
	s_lshl_b32 s12, s12, 13
	v_and_b32_e32 v8, 32, v8
	s_add_i32 m0, s72, 0x18000
	v_lshl_add_u64 v[18:19], v[18:19], 0, s[94:95]
	v_lshl_add_u64 v[22:23], s[64:65], 0, v[0:1]
	v_bitop3_b32 v28, v27, s12, v8 bitop3:0xde
	s_lshl_b32 s12, s90, 12
	s_barrier
	global_load_lds_dwordx4 v[18:19], off
	v_lshl_add_u64 v[18:19], v[20:21], 0, s[94:95]
	s_add_i32 m0, s72, 0x1a000
	s_add_i32 s76, s72, 0x8000
	s_add_i32 s77, s72, 0xa000
	v_lshl_add_u64 v[24:25], s[64:65], 0, v[2:3]
	global_load_lds_dwordx4 v[18:19], off
	v_lshl_add_u64 v[18:19], v[22:23], 0, s[94:95]
	s_mov_b32 m0, s76
	s_add_u32 s14, s66, 0x40080
	global_load_lds_dwordx4 v[18:19], off
	v_lshl_add_u64 v[18:19], v[24:25], 0, s[94:95]
	s_mov_b32 m0, s77
	s_addc_u32 s15, s67, 0
	global_load_lds_dwordx4 v[18:19], off
	s_add_i32 m0, s72, 0x1c000
	v_lshl_add_u64 v[18:19], s[14:15], 0, v[0:1]
	global_load_lds_dwordx4 v[18:19], off
	v_lshl_add_u64 v[18:19], s[14:15], 0, v[2:3]
	s_add_i32 m0, s72, 0x1e000
	v_bitop3_b32 v179, v27, s12, v8 bitop3:0xde
	global_load_lds_dwordx4 v[18:19], off
	v_lshlrev_b32_e32 v8, 2, v26
	v_lshl_or_b32 v222, s90, 5, v8
	v_lshlrev_b32_e32 v8, 13, v13
	v_and_b32_e32 v8, 0x7fffc000, v8
	v_lshl_add_u32 v8, v14, 10, v8
	v_or_b32_e32 v8, v8, v15
	v_add_lshl_u32 v14, v8, v16, 1
	v_lshlrev_b32_e32 v8, 13, v9
	v_and_b32_e32 v8, 0x7fffc000, v8
	v_lshl_add_u32 v8, v10, 10, v8
	v_or_b32_e32 v8, v8, v11
	v_mov_b32_e32 v15, v1
	s_mov_b64 s[14:15], 0x40080
	v_add_lshl_u32 v8, v8, v12, 1
	v_mov_b32_e32 v9, v1
	v_lshl_add_u64 v[136:137], v[14:15], 0, s[14:15]
	v_lshl_add_u64 v[138:139], v[8:9], 0, s[14:15]
	v_readlane_b32 s14, v253, 51
	v_or_b32_e32 v176, s26, v17
	s_waitcnt vmcnt(6)
	s_addk_i32 s26, 0x80
	v_readlane_b32 s15, v253, 52
	v_or_b32_e32 v226, s26, v17
	s_mov_b32 s97, s14
	v_readlane_b32 s14, v255, 21
	v_cmp_eq_u32_e64 s[44:45], 0, v26
	v_or_b32_e32 v223, 16, v176
	v_or_b32_e32 v224, 32, v176
	v_or_b32_e32 v225, 48, v176
	v_or_b32_e32 v227, 16, v226
	v_or_b32_e32 v228, 32, v226
	v_or_b32_e32 v229, 48, v226
	v_mov_b32_e32 v231, 0
	v_add_u32_e32 v230, 0, v28
	v_readlane_b32 s96, v253, 27
	s_mov_b32 s78, s14
	s_barrier
	v_readlane_b32 s15, v255, 22
	s_branch .LBB0_147

; __device__ __forceinline__ int prow0(int pm) { return (pm >> 4) * LP + PADR + (pm & 15) * 256; }
;     __device__ __forceinline__ void prep(int pm, int par, LAS unsigned char* lds) const { if (fold) prep_rowstats(stat, pm, par, lds); }
;     __device__ __forceinline__ void prep(int pm, int par, LAS unsigned char* lds) const { if (!ident) prep_rowstats(stat, pm, par, lds); }
;     __device__ __forceinline__ void prep(int pm, int par, LAS unsigned char* lds) const { prep_rowstats(stat, pm, par, lds); }
; #define G_STAGE(bufoff, gbase) do { _Pragma("unroll") for (int _i = 0; _i < 2; ++_i) \
;         __builtin_amdgcn_global_load_lds((const unsigned*)((const char*)(gbase) + voff[_i]), (LAS unsigned*)(lds + (bufoff) + ldsw + _i * 8192), 16, 0, 0); } while (0)
; #define G_WAIT_V(n) asm volatile("s_waitcnt vmcnt(" #n ")" ::: "memory")
; #define G_BAR __builtin_amdgcn_s_barrier()
; template <class Epi>
; __device__ __forceinline__ void gemm_phase(LAS unsigned char* lds, const bf16_t* Ag, const bf16_t* Btg, const int K, const int nM, const int nN, const Epi& E) {
;     ...
;     for (int i = 0; i < 2; ++i) { int R, C; stage_rc(tid * 16 + i * 8192, R, C); voff[i] = (unsigned)(R * K + C) * 2u; }
;     const size_t kstep = 128, hstep = (size_t)128 * K * 2, tstep = 2 * hstep;
;     const unsigned ldsw = (unsigned)wid * 1024u;
;     const int aoff = lds_byte(wr * 64 + fr, fq * 8), boff = lds_byte(wc * 32 + fr, fq * 8);
;     ...
;     const size_t rstep = (size_t)K * 2;
;     const char* cA = (const char*)Ag + (size_t)prow0(pm) * rstep; const char* cB = (const char*)Btg + (size_t)pn * tstep;
;     E.prep(pm, par, lds);
;     G_STAGE(G_SB(0, 0), cB); G_STAGE(G_SA(0, 0), cA); G_STAGE(G_SB(0, 1), cB + hstep); G_STAGE(G_SA(0, 1), cA + hstep);
;     if (wr == 1) G_BAR;
;     G_WAIT_V(4); G_BAR;
;     G_STAGE(G_SB(1, 0), cB + kstep); G_STAGE(G_SA(1, 0), cA + kstep); G_STAGE(G_SB(1, 1), cB + hstep + kstep);
;     G_WAIT_V(6); G_BAR;
.LBB0_736:
	s_waitcnt vmcnt(0)
	v_bfe_u32 v26, v9, 4, 2
	v_lshl_add_u64 v[18:19], s[58:59], 0, v[0:1]
	v_mov_b32_e32 v3, v1
	v_and_b32_e32 v17, 15, v9
	v_lshlrev_b32_e32 v27, 4, v26
	v_lshlrev_b32_e32 v9, 2, v9
	v_lshl_add_u64 v[20:21], s[58:59], 0, v[2:3]
	s_and_b32 s90, s14, 3
	s_lshl_b32 s24, s12, 6
	v_lshl_or_b32 v27, v17, 6, v27
	s_lshl_b32 s12, s12, 13
	v_and_b32_e32 v9, 32, v9
	s_add_i32 m0, s66, 0x18000
	v_lshl_add_u64 v[18:19], v[18:19], 0, s[94:95]
	v_lshl_add_u64 v[22:23], s[56:57], 0, v[0:1]
	v_bitop3_b32 v28, v27, s12, v9 bitop3:0xde
	s_lshl_b32 s12, s90, 12
	s_barrier
	global_load_lds_dwordx4 v[18:19], off
	v_lshl_add_u64 v[18:19], v[20:21], 0, s[94:95]
	s_add_i32 m0, s66, 0x1a000
	s_add_i32 s70, s66, 0x8000
	s_add_i32 s71, s66, 0xa000
	v_lshl_add_u64 v[24:25], s[56:57], 0, v[2:3]
	global_load_lds_dwordx4 v[18:19], off
	v_lshl_add_u64 v[18:19], v[22:23], 0, s[94:95]
	s_mov_b32 m0, s70
	s_add_u32 s14, s58, 0x100080
	global_load_lds_dwordx4 v[18:19], off
	v_lshl_add_u64 v[18:19], v[24:25], 0, s[94:95]
	s_mov_b32 m0, s71
	s_addc_u32 s15, s59, 0
	global_load_lds_dwordx4 v[18:19], off
	s_add_i32 m0, s66, 0x1c000
	v_lshl_add_u64 v[18:19], s[14:15], 0, v[0:1]
	global_load_lds_dwordx4 v[18:19], off
	v_lshl_add_u64 v[18:19], s[14:15], 0, v[2:3]
	s_add_i32 m0, s66, 0x1e000
	v_bitop3_b32 v165, v27, s12, v9 bitop3:0xde
	global_load_lds_dwordx4 v[18:19], off
	v_lshlrev_b32_e32 v9, 2, v26
	v_lshl_or_b32 v166, s90, 5, v9
	v_lshlrev_b32_e32 v9, 15, v13
	v_lshlrev_b32_e32 v8, 15, v8
	v_and_b32_e32 v9, 0x7fff0000, v9
	v_and_b32_e32 v8, 0x7fff0000, v8
	v_lshl_add_u32 v9, v14, 12, v9
	v_lshl_add_u32 v8, v10, 12, v8
	v_or_b32_e32 v9, v9, v15
	v_or_b32_e32 v8, v8, v11
	v_add_lshl_u32 v14, v9, v16, 1
	v_mov_b32_e32 v15, v1
	s_mov_b64 s[14:15], 0x100080
	v_add_lshl_u32 v8, v8, v12, 1
	v_mov_b32_e32 v9, v1
	v_lshl_add_u64 v[136:137], v[14:15], 0, s[14:15]
	v_lshl_add_u64 v[138:139], v[8:9], 0, s[14:15]
	v_readlane_b32 s14, v253, 51
	v_or_b32_e32 v164, s24, v17
	s_waitcnt vmcnt(6)
	s_addk_i32 s24, 0x80
	v_readlane_b32 s15, v253, 52
	v_or_b32_e32 v170, s24, v17
	s_mov_b32 s76, s14
	v_readlane_b32 s14, v255, 21
	s_mov_b32 s72, 0
	v_cmp_eq_u32_e64 s[44:45], 0, v26
	v_or_b32_e32 v167, 16, v164
	v_or_b32_e32 v168, 32, v164
	v_or_b32_e32 v169, 48, v164
	v_or_b32_e32 v171, 16, v170
	v_or_b32_e32 v172, 32, v170
	v_or_b32_e32 v173, 48, v170
	v_add_u32_e32 v174, 0, v28
	v_readlane_b32 s74, v253, 27
	s_mov_b32 s73, s14
	s_barrier
	v_readlane_b32 s15, v255, 22
	s_branch .LBB0_738

; __device__ __forceinline__ int prow0(int pm) { return (pm >> 4) * LP + PADR + (pm & 15) * 256; }
;     __device__ __forceinline__ void prep(int pm, int par, LAS unsigned char* lds) const { if (fold) prep_rowstats(stat, pm, par, lds); }
;     __device__ __forceinline__ void prep(int pm, int par, LAS unsigned char* lds) const { if (!ident) prep_rowstats(stat, pm, par, lds); }
;     __device__ __forceinline__ void prep(int pm, int par, LAS unsigned char* lds) const { prep_rowstats(stat, pm, par, lds); }
; #define G_STAGE(bufoff, gbase) do { _Pragma("unroll") for (int _i = 0; _i < 2; ++_i) \
;         __builtin_amdgcn_global_load_lds((const unsigned*)((const char*)(gbase) + voff[_i]), (LAS unsigned*)(lds + (bufoff) + ldsw + _i * 8192), 16, 0, 0); } while (0)
; #define G_WAIT_V(n) asm volatile("s_waitcnt vmcnt(" #n ")" ::: "memory")
; #define G_BAR __builtin_amdgcn_s_barrier()
; template <class Epi>
; __device__ __forceinline__ void gemm_phase(LAS unsigned char* lds, const bf16_t* Ag, const bf16_t* Btg, const int K, const int nM, const int nN, const Epi& E) {
;     ...
;     for (int i = 0; i < 2; ++i) { int R, C; stage_rc(tid * 16 + i * 8192, R, C); voff[i] = (unsigned)(R * K + C) * 2u; }
;     const size_t kstep = 128, hstep = (size_t)128 * K * 2, tstep = 2 * hstep;
;     const unsigned ldsw = (unsigned)wid * 1024u;
;     const int aoff = lds_byte(wr * 64 + fr, fq * 8), boff = lds_byte(wc * 32 + fr, fq * 8);
;     ...
;     const size_t rstep = (size_t)K * 2;
;     const char* cA = (const char*)Ag + (size_t)prow0(pm) * rstep; const char* cB = (const char*)Btg + (size_t)pn * tstep;
;     E.prep(pm, par, lds);
;     G_STAGE(G_SB(0, 0), cB); G_STAGE(G_SA(0, 0), cA); G_STAGE(G_SB(0, 1), cB + hstep); G_STAGE(G_SA(0, 1), cA + hstep);
;     if (wr == 1) G_BAR;
;     G_WAIT_V(4); G_BAR;
;     G_STAGE(G_SB(1, 0), cB + kstep); G_STAGE(G_SA(1, 0), cA + kstep); G_STAGE(G_SB(1, 1), cB + hstep + kstep);
;     G_WAIT_V(6); G_BAR;
.LBB0_839:
	s_lshl_b32 s15, s15, 5
	s_waitcnt lgkmcnt(0)
	s_and_b32 s24, s15, 0x60
	s_add_i32 m0, s60, 0x18000
	v_lshl_add_u64 v[14:15], v[14:15], 0, s[94:95]
	s_lshl_b32 s22, s14, 6
	s_lshl_b32 s23, s14, 13
	s_lshl_b32 s25, s24, 7
	s_barrier
	global_load_lds_dwordx4 v[14:15], off
	v_lshl_add_u64 v[12:13], v[12:13], 0, s[94:95]
	s_add_i32 m0, s60, 0x1a000
	s_add_i32 s64, s60, 0x8000
	s_add_i32 s65, s60, 0xa000
	global_load_lds_dwordx4 v[12:13], off
	v_lshl_add_u64 v[10:11], v[10:11], 0, s[94:95]
	s_mov_b32 m0, s64
	s_add_u32 s14, s52, 0x40080
	global_load_lds_dwordx4 v[10:11], off
	v_lshl_add_u64 v[8:9], v[8:9], 0, s[94:95]
	s_mov_b32 m0, s65
	s_addc_u32 s15, s53, 0
	global_load_lds_dwordx4 v[8:9], off
	s_add_i32 m0, s60, 0x1c000
	v_lshl_add_u64 v[8:9], s[14:15], 0, v[0:1]
	global_load_lds_dwordx4 v[8:9], off
	v_lshl_add_u64 v[8:9], s[14:15], 0, v[2:3]
	s_add_i32 m0, s60, 0x1e000
	v_lshlrev_b32_e32 v11, 2, v16
	global_load_lds_dwordx4 v[8:9], off
	v_and_b32_e32 v8, 15, v16
	v_bfe_u32 v9, v16, 4, 2
	v_or_b32_e32 v176, s22, v8
	v_lshlrev_b32_e32 v10, 4, v9
	s_addk_i32 s22, 0x80
	v_lshl_or_b32 v10, v8, 6, v10
	v_or_b32_e32 v193, s22, v8
	v_lshlrev_b32_e32 v8, 14, v20
	v_and_b32_e32 v8, 0xffff8000, v8
	v_lshl_or_b32 v197, v9, 2, s24
	v_lshl_add_u32 v8, v21, 11, v8
	v_and_b32_e32 v9, 1, v20
	v_lshl_or_b32 v8, v9, 6, v8
	v_lshl_add_u32 v168, v22, 1, v8
	v_lshlrev_b32_e32 v8, 14, v17
	v_and_b32_e32 v8, 0xffff8000, v8
	v_readlane_b32 s14, v253, 51
	v_and_b32_e32 v11, 32, v11
	s_waitcnt vmcnt(6)
	v_lshl_add_u32 v8, v18, 11, v8
	v_and_b32_e32 v9, 1, v17
	v_readlane_b32 s15, v253, 52
	v_bitop3_b32 v12, v10, s23, v11 bitop3:0xde
	v_lshl_or_b32 v8, v9, 6, v8
	s_mov_b32 s69, s14
	v_readlane_b32 s14, v255, 21
	v_bitop3_b32 v179, v10, s25, v11 bitop3:0xde
	v_or_b32_e32 v190, 16, v176
	v_or_b32_e32 v191, 32, v176
	v_or_b32_e32 v192, 48, v176
	v_or_b32_e32 v194, 16, v193
	v_or_b32_e32 v195, 32, v193
	v_or_b32_e32 v196, 48, v193
	v_mov_b32_e32 v169, v1
	v_lshl_add_u32 v170, v19, 1, v8
	v_mov_b32_e32 v171, v1
	v_mov_b32_e32 v223, 0
	v_add_u32_e32 v222, 0, v12
	v_readlane_b32 s68, v253, 27
	s_mov_b32 s66, s14
	s_barrier
	v_readlane_b32 s15, v255, 22
	s_branch .LBB0_842
